# nt cache-policy hint on the once-read row-pass streams (P6/P9/P12 next-row prefetch loads, P0 rms x loads) and on P12's y stores
# baseline (speedup 1.0000x reference)
; __device__ __forceinline__ unsigned pk2(float lo, float hi) { return pg8::cvt_pk_bf16(lo, hi); }
; __device__ __forceinline__ void rms_row_to_bf16(const float* xr, const float* g, bf16* orow, int lane) {
;     f32x4 v[8]; float s = 0.f;
; #pragma unroll
;     for (int j = 0; j < 4; ++j) { v[2 * j] = *(const f32x4*)(xr + j * 512 + lane * 8); v[2 * j + 1] = *(const f32x4*)(xr + j * 512 + lane * 8 + 4); }
; #pragma unroll
;     for (int j = 0; j < 8; ++j) s += (v[j].x * v[j].x + v[j].y * v[j].y) + (v[j].z * v[j].z + v[j].w * v[j].w);
;     const float rstd = rsqrtf(wave_sum(s) * (1.f / DM) + EPS);
; #pragma unroll
;     for (int j = 0; j < 4; ++j) {
;         const f32x4 g0 = *(const f32x4*)(g + j * 512 + lane * 8), g1 = *(const f32x4*)(g + j * 512 + lane * 8 + 4);
;         const f32x4 a = v[2 * j] * rstd * g0, b = v[2 * j + 1] * rstd * g1;
;         v4u o; o.x = pk2(a.x, a.y); o.y = pk2(a.z, a.w); o.z = pk2(b.x, b.y); o.w = pk2(b.z, b.w);
;         *(v4u*)(orow + j * 512 + lane * 8) = o;
;     }
; }
.LBB0_241:
	v_lshl_add_u64 v[0:1], s[22:23], 0, v[16:17]
	global_load_dwordx4 v[34:37], v16, s[22:23] nt
	global_load_dwordx4 v[38:41], v16, s[22:23] offset:16 nt
	global_load_dwordx4 v[42:45], v16, s[22:23] offset:2048 nt
	global_load_dwordx4 v[46:49], v16, s[22:23] offset:2064 nt
	v_add_co_u32_e32 v4, vcc, 0x1000, v0
	v_lshl_add_u64 v[2:3], v[0:1], 0, s[4:5]
	s_nop 0
	v_addc_co_u32_e32 v5, vcc, 0, v1, vcc
	global_load_dwordx4 v[12:15], v[4:5], off nt
	global_load_dwordx4 v[8:11], v[2:3], off offset:16 nt
	v_lshl_add_u64 v[0:1], v[0:1], 0, s[8:9]
	global_load_dwordx4 v[0:3], v[0:1], off offset:16 nt
	s_nop 0
	global_load_dwordx4 v[4:7], v[4:5], off offset:2048 nt
	s_nop 0
	s_lshl_b64 s[20:21], s[20:21], 12
	s_add_u32 s18, s18, s2
	s_addc_u32 s19, s19, s3
	s_add_u32 s12, s12, s16
	s_addc_u32 s13, s13, s17
	s_cmp_lt_i32 s18, 0x8400
	s_waitcnt vmcnt(7)
	v_mov_b32_e32 v60, v35
	s_waitcnt vmcnt(6)
	v_mov_b32_e32 v61, v39
	v_mov_b32_e32 v64, v37
	v_mov_b32_e32 v65, v41
	v_mov_b32_e32 v58, v34
	v_mov_b32_e32 v59, v38
	v_mov_b32_e32 v62, v36
	v_mov_b32_e32 v63, v40
	s_waitcnt vmcnt(5)
	v_pk_mul_f32 v[66:67], v[44:45], v[44:45]
	v_pk_mul_f32 v[68:69], v[42:43], v[42:43]
	v_pk_mul_f32 v[60:61], v[60:61], v[60:61]
	v_pk_mul_f32 v[64:65], v[64:65], v[64:65]
	s_waitcnt vmcnt(4)
	v_mul_f32_e32 v70, v47, v47
	v_pk_mov_b32 v[74:75], v[68:69], v[66:67] op_sel:[1,0]
	v_mov_b32_e32 v69, v67
	v_pk_fma_f32 v[58:59], v[58:59], v[58:59], v[60:61]
	v_pk_fma_f32 v[60:61], v[62:63], v[62:63], v[64:65]
	v_mul_f32_e32 v72, v49, v49
	v_pk_fma_f32 v[66:67], v[46:47], v[46:47], v[70:71] op_sel_hi:[1,1,0]
	v_pk_add_f32 v[62:63], v[74:75], v[68:69]
	v_pk_add_f32 v[58:59], v[58:59], v[60:61]
	v_pk_fma_f32 v[70:71], v[48:49], v[48:49], v[72:73] op_sel_hi:[1,1,0]
	s_waitcnt vmcnt(3)
	v_mul_f32_e32 v33, v12, v12
	v_mul_f32_e32 v67, v13, v13
	v_mul_f32_e32 v69, v14, v14
	v_pk_add_f32 v[60:61], v[62:63], v[62:63] op_sel:[0,1] op_sel_hi:[1,0]
	v_pk_add_f32 v[58:59], v[58:59], v[58:59] op_sel:[0,1] op_sel_hi:[1,0]
	v_mul_f32_e32 v71, v15, v15
	s_waitcnt vmcnt(2)
	v_pk_mul_f32 v[62:63], v[10:11], v[10:11]
	v_pk_mul_f32 v[64:65], v[8:9], v[8:9]
	v_mov_b32_e32 v61, v67
	v_mov_b32_e32 v67, v69
	v_mov_b32_e32 v59, v33
	v_pk_mov_b32 v[74:75], v[64:65], v[62:63] op_sel:[1,0]
	v_mov_b32_e32 v65, v63
	v_pk_add_f32 v[66:67], v[66:67], v[70:71]
	v_pk_add_f32 v[58:59], v[58:59], v[60:61]
	s_waitcnt vmcnt(1)
	v_mul_f32_e32 v73, v0, v0
	s_waitcnt vmcnt(0)
	v_mul_f32_e32 v68, v5, v5
	v_mul_f32_e32 v72, v7, v7
	v_pk_add_f32 v[64:65], v[74:75], v[64:65]
	v_pk_add_f32 v[58:59], v[58:59], v[66:67]
	v_mul_f32_e32 v76, v1, v1
	v_mul_f32_e32 v77, v2, v2
	v_mul_f32_e32 v78, v3, v3
	v_pk_fma_f32 v[62:63], v[4:5], v[4:5], v[68:69] op_sel_hi:[1,1,0]
	v_pk_fma_f32 v[68:69], v[6:7], v[6:7], v[72:73] op_sel_hi:[1,1,0]
	v_pk_add_f32 v[60:61], v[64:65], v[64:65] op_sel:[0,1] op_sel_hi:[1,0]
	v_pk_add_f32 v[58:59], v[58:59], v[58:59] op_sel:[0,1] op_sel_hi:[1,0]
	v_mov_b32_e32 v63, v77
	v_mov_b32_e32 v69, v78
	v_mov_b32_e32 v61, v76
	v_mov_b32_e32 v59, v73
	v_pk_add_f32 v[62:63], v[62:63], v[68:69]
	v_pk_add_f32 v[58:59], v[58:59], v[60:61]
	s_nop 0
	v_pk_add_f32 v[58:59], v[58:59], v[62:63]
	s_nop 0
	v_add_f32_e32 v33, v58, v59
	ds_bpermute_b32 v58, v26, v33
	s_waitcnt lgkmcnt(0)
	v_add_f32_e32 v33, v33, v58
	ds_bpermute_b32 v58, v27, v33
	s_waitcnt lgkmcnt(0)
	v_add_f32_e32 v33, v33, v58
	ds_bpermute_b32 v58, v28, v33
	s_waitcnt lgkmcnt(0)
	v_add_f32_e32 v33, v33, v58
	ds_bpermute_b32 v58, v29, v33
	s_waitcnt lgkmcnt(0)
	v_add_f32_e32 v33, v33, v58
	ds_bpermute_b32 v58, v30, v33
	s_waitcnt lgkmcnt(0)
	v_add_f32_e32 v33, v33, v58
	ds_bpermute_b32 v58, v31, v33
	s_waitcnt lgkmcnt(0)
	v_add_f32_e32 v33, v33, v58
	v_fmamk_f32 v33, v33, 0x3a000000, v32
	v_mul_f32_e32 v58, 0x4b800000, v33
	v_cmp_gt_f32_e32 vcc, s6, v33
	s_nop 1
	v_cndmask_b32_e32 v33, v33, v58, vcc
	v_rsq_f32_e32 v33, v33
	v_lshl_add_u64 v[58:59], v[20:21], 0, s[20:21]
	v_mul_f32_e32 v60, 0x45800000, v33
	v_cndmask_b32_e32 v60, v33, v60, vcc
	v_pk_mul_f32 v[34:35], v[34:35], v[60:61] op_sel_hi:[1,0]
	v_pk_mul_f32 v[36:37], v[36:37], v[60:61] op_sel_hi:[1,0]
	v_pk_mul_f32 v[38:39], v[38:39], v[60:61] op_sel_hi:[1,0]
	v_pk_mul_f32 v[40:41], v[40:41], v[60:61] op_sel_hi:[1,0]
	s_waitcnt vmcnt(0)
	v_pk_mul_f32 v[36:37], v[176:177], v[36:37]
	v_pk_mul_f32 v[34:35], v[174:175], v[34:35]
	v_pk_mul_f32 v[40:41], v[172:173], v[40:41]
	v_pk_mul_f32 v[38:39], v[170:171], v[38:39]
	v_cvt_pk_bf16_f32 v34, v34, v35
	v_cvt_pk_bf16_f32 v35, v36, v37
	v_pk_mul_f32 v[42:43], v[42:43], v[60:61] op_sel_hi:[1,0]
	v_cvt_pk_bf16_f32 v36, v38, v39
	v_cvt_pk_bf16_f32 v37, v40, v41
	global_store_dwordx4 v[58:59], v[34:37], off
	v_pk_mul_f32 v[44:45], v[44:45], v[60:61] op_sel_hi:[1,0]
	v_pk_mul_f32 v[46:47], v[46:47], v[60:61] op_sel_hi:[1,0]
	v_pk_mul_f32 v[48:49], v[48:49], v[60:61] op_sel_hi:[1,0]
	v_pk_mul_f32 v[12:13], v[12:13], v[60:61] op_sel_hi:[1,0]
	v_pk_mul_f32 v[8:9], v[8:9], v[60:61] op_sel_hi:[1,0]
	v_pk_mul_f32 v[10:11], v[10:11], v[60:61] op_sel_hi:[1,0]
	v_pk_mul_f32 v[14:15], v[14:15], v[60:61] op_sel_hi:[1,0]
	v_pk_mul_f32 v[4:5], v[4:5], v[60:61] op_sel_hi:[1,0]
	v_pk_mul_f32 v[0:1], v[0:1], v[60:61] op_sel_hi:[1,0]
	v_pk_mul_f32 v[2:3], v[2:3], v[60:61] op_sel_hi:[1,0]
	v_pk_mul_f32 v[6:7], v[6:7], v[60:61] op_sel_hi:[1,0]
	v_pk_mul_f32 v[36:37], v[180:181], v[44:45]
	v_pk_mul_f32 v[34:35], v[178:179], v[42:43]
	v_pk_mul_f32 v[40:41], v[184:185], v[48:49]
	v_pk_mul_f32 v[38:39], v[182:183], v[46:47]
	v_cvt_pk_bf16_f32 v34, v34, v35
	v_cvt_pk_bf16_f32 v35, v36, v37
	s_nop 0
	v_cvt_pk_bf16_f32 v36, v38, v39
	v_cvt_pk_bf16_f32 v37, v40, v41
	global_store_dwordx4 v[58:59], v[34:37], off offset:1024
	s_nop 1
	v_pk_mul_f32 v[12:13], v[12:13], v[186:187]
	v_pk_mul_f32 v[34:35], v[10:11], v[192:193]
	v_pk_mul_f32 v[10:11], v[8:9], v[190:191]
	v_pk_mul_f32 v[14:15], v[14:15], v[188:189]
	v_cvt_pk_bf16_f32 v8, v12, v13
	s_nop 0
	v_cvt_pk_bf16_f32 v9, v14, v15
	v_cvt_pk_bf16_f32 v10, v10, v11
	v_cvt_pk_bf16_f32 v11, v34, v35
	global_store_dwordx4 v[58:59], v[8:11], off offset:2048
	s_nop 1
	v_pk_mul_f32 v[4:5], v[4:5], v[194:195]
	v_pk_mul_f32 v[8:9], v[2:3], v[200:201]
	v_pk_mul_f32 v[2:3], v[0:1], v[198:199]
	v_pk_mul_f32 v[6:7], v[6:7], v[196:197]
	v_cvt_pk_bf16_f32 v0, v4, v5
	s_nop 0
	v_cvt_pk_bf16_f32 v1, v6, v7
	v_cvt_pk_bf16_f32 v2, v2, v3
	v_cvt_pk_bf16_f32 v3, v8, v9
	global_store_dwordx4 v[58:59], v[0:3], off offset:3072
	s_cbranch_scc0 .LBB0_244

; #define RP_LOAD4(dst, ptr) do { _Pragma("unroll") for (int j = 0; j < 4; ++j) dst[j] = *(const v4u*)((ptr) + j * 512 + lane * 8); } while (0)
; #define RP_LOADX(dst, ptr) do { _Pragma("unroll") for (int j = 0; j < 4; ++j) { dst[2 * j] = *(const f32x4*)((ptr) + j * 512 + lane * 8); dst[2 * j + 1] = *(const f32x4*)((ptr) + j * 512 + lane * 8 + 4); } } while (0)
; __global__ void __launch_bounds__(NTHR, 2) fwd_megakernel(Args args) {
;     ...
;             for (; m < MP; m += NGW) {
;                 const int m2 = m + NGW;
;                 if (m2 < MP) { RP_LOAD4(mnx, Z + (size_t)m2 * DM); RP_LOADX(xnx, x_prompt + (size_t)m2 * DM); }
.LBB0_1012:
	s_add_i32 s23, s23, s34
	s_cmpk_gt_i32 s23, 0x7fff
	s_cselect_b64 s[20:21], -1, 0
	s_and_b64 vcc, exec, s[20:21]
	s_cbranch_vccnz .LBB0_1011
	v_lshl_add_u64 v[24:25], s[16:17], 0, v[96:97]
	v_add_co_u32_e32 v40, vcc, 0x15800000, v24
	v_lshl_add_u64 v[48:49], v[104:105], 0, s[18:19]
	s_nop 0
	v_addc_co_u32_e32 v41, vcc, 0, v25, vcc
	v_add_co_u32_e32 v56, vcc, 0xfffff000, v104
	global_load_dwordx4 v[24:27], v[40:41], off nt
	global_load_dwordx4 v[28:31], v[40:41], off offset:1024 nt
	global_load_dwordx4 v[36:39], v[40:41], off offset:2048 nt
	s_nop 0
	global_load_dwordx4 v[40:43], v[40:41], off offset:3072 nt
	v_addc_co_u32_e32 v57, vcc, -1, v105, vcc
	global_load_dwordx4 v[52:55], v[56:57], off offset:-2064 nt
	s_nop 0
	global_load_dwordx4 v[48:51], v[48:49], off offset:16 nt
	s_nop 0
	global_load_dwordx4 v[60:63], v[56:57], off offset:-16 nt
	s_nop 0
	global_load_dwordx4 v[56:59], v[104:105], off offset:-4096 nt
	global_load_dwordx4 v[64:67], v[104:105], off offset:-2048 nt
	global_load_dwordx4 v[68:71], v[104:105], off offset:-2064 nt
	global_load_dwordx4 v[72:75], v[104:105], off nt
	global_load_dwordx4 v[76:79], v[104:105], off offset:-16 nt
	s_branch .LBB0_1011

.LBB0_1246:
	s_add_i32 s20, s20, s34
	s_cmpk_gt_i32 s20, 0x7fff
	s_cselect_b64 s[16:17], -1, 0
	s_and_b64 vcc, exec, s[16:17]
	s_cbranch_vccnz .LBB0_1245
	v_lshl_add_u64 v[0:1], s[6:7], 0, v[64:65]
	v_add_co_u32_e32 v16, vcc, 0x8100000, v0
	v_lshl_add_u64 v[74:75], s[8:9], 0, v[64:65]
	s_nop 0
	v_addc_co_u32_e32 v17, vcc, 0, v1, vcc
	global_load_dwordx4 v[12:15], v[16:17], off nt
	global_load_dwordx4 v[8:11], v[16:17], off offset:1024 nt
	global_load_dwordx4 v[4:7], v[16:17], off offset:2048 nt
	global_load_dwordx4 v[0:3], v[16:17], off offset:3072 nt
	global_load_dwordx4 v[28:31], v[74:75], off nt
	global_load_dwordx4 v[24:27], v[74:75], off offset:1024 nt
	global_load_dwordx4 v[20:23], v[74:75], off offset:2048 nt
	s_nop 0
	global_load_dwordx4 v[16:19], v[74:75], off offset:3072 nt
	s_branch .LBB0_1245

.LBB0_1396:
	v_lshlrev_b32_e32 v96, 16, v60
	v_and_b32_e32 v97, 0xffff0000, v60
	v_pk_mul_f32 v[98:99], v[96:97], v[96:97]
	v_lshlrev_b32_e32 v60, 16, v61
	v_and_b32_e32 v61, 0xffff0000, v61
	v_pk_mul_f32 v[100:101], v[60:61], v[60:61]
	v_add_f32_e32 v81, v98, v99
	v_lshlrev_b32_e32 v90, 16, v62
	v_and_b32_e32 v91, 0xffff0000, v62
	v_add_f32_e32 v81, v81, v100
	v_pk_mul_f32 v[92:93], v[90:91], v[90:91]
	v_add_f32_e32 v81, v81, v101
	v_lshlrev_b32_e32 v62, 16, v63
	v_and_b32_e32 v63, 0xffff0000, v63
	v_add_f32_e32 v81, v81, v92
	v_pk_mul_f32 v[94:95], v[62:63], v[62:63]
	v_add_f32_e32 v81, v81, v93
	v_lshlrev_b32_e32 v108, 16, v56
	v_and_b32_e32 v109, 0xffff0000, v56
	v_add_f32_e32 v81, v81, v94
	v_pk_mul_f32 v[110:111], v[108:109], v[108:109]
	v_add_f32_e32 v81, v81, v95
	v_lshlrev_b32_e32 v56, 16, v57
	v_and_b32_e32 v57, 0xffff0000, v57
	v_add_f32_e32 v81, v81, v110
	v_pk_mul_f32 v[112:113], v[56:57], v[56:57]
	v_add_f32_e32 v81, v81, v111
	v_lshlrev_b32_e32 v102, 16, v58
	v_and_b32_e32 v103, 0xffff0000, v58
	v_add_f32_e32 v81, v81, v112
	v_pk_mul_f32 v[104:105], v[102:103], v[102:103]
	v_add_f32_e32 v81, v81, v113
	v_lshlrev_b32_e32 v58, 16, v59
	v_and_b32_e32 v59, 0xffff0000, v59
	v_add_f32_e32 v81, v81, v104
	v_pk_mul_f32 v[106:107], v[58:59], v[58:59]
	v_add_f32_e32 v81, v81, v105
	v_lshlrev_b32_e32 v120, 16, v52
	v_and_b32_e32 v121, 0xffff0000, v52
	v_add_f32_e32 v81, v81, v106
	v_pk_mul_f32 v[122:123], v[120:121], v[120:121]
	v_add_f32_e32 v81, v81, v107
	v_lshlrev_b32_e32 v52, 16, v53
	v_and_b32_e32 v53, 0xffff0000, v53
	v_add_f32_e32 v81, v81, v122
	v_pk_mul_f32 v[124:125], v[52:53], v[52:53]
	v_add_f32_e32 v81, v81, v123
	v_lshlrev_b32_e32 v114, 16, v54
	v_and_b32_e32 v115, 0xffff0000, v54
	v_add_f32_e32 v81, v81, v124
	v_pk_mul_f32 v[116:117], v[114:115], v[114:115]
	v_add_f32_e32 v81, v81, v125
	v_lshlrev_b32_e32 v54, 16, v55
	v_and_b32_e32 v55, 0xffff0000, v55
	v_add_f32_e32 v81, v81, v116
	v_pk_mul_f32 v[118:119], v[54:55], v[54:55]
	v_add_f32_e32 v81, v81, v117
	v_lshlrev_b32_e32 v132, 16, v48
	v_and_b32_e32 v133, 0xffff0000, v48
	v_add_f32_e32 v81, v81, v118
	v_pk_mul_f32 v[134:135], v[132:133], v[132:133]
	v_add_f32_e32 v81, v81, v119
	v_lshlrev_b32_e32 v136, 16, v49
	v_and_b32_e32 v137, 0xffff0000, v49
	v_add_f32_e32 v81, v81, v134
	v_pk_mul_f32 v[48:49], v[136:137], v[136:137]
	v_add_f32_e32 v81, v81, v135
	v_lshlrev_b32_e32 v126, 16, v50
	v_and_b32_e32 v127, 0xffff0000, v50
	v_add_f32_e32 v48, v81, v48
	v_pk_mul_f32 v[128:129], v[126:127], v[126:127]
	v_add_f32_e32 v48, v48, v49
	v_lshlrev_b32_e32 v130, 16, v51
	v_and_b32_e32 v131, 0xffff0000, v51
	v_add_f32_e32 v48, v48, v128
	v_pk_mul_f32 v[50:51], v[130:131], v[130:131]
	v_add_f32_e32 v48, v48, v129
	v_add_f32_e32 v48, v48, v50
	v_add_f32_e32 v48, v48, v51
	ds_bpermute_b32 v49, v74, v48
	v_and_b32_e32 v51, 0xffff0000, v47
	v_and_b32_e32 v93, 0xffff0000, v45
	v_lshl_add_u64 v[72:73], v[72:73], 0, s[2:3]
	s_waitcnt lgkmcnt(0)
	v_add_f32_e32 v48, v48, v49
	ds_bpermute_b32 v49, v75, v48
	s_waitcnt lgkmcnt(0)
	v_add_f32_e32 v48, v48, v49
	ds_bpermute_b32 v49, v76, v48
	s_waitcnt lgkmcnt(0)
	v_add_f32_e32 v48, v48, v49
	ds_bpermute_b32 v49, v77, v48
	s_waitcnt lgkmcnt(0)
	v_add_f32_e32 v49, v48, v49
	ds_bpermute_b32 v50, v78, v49
	v_lshlrev_b32_e32 v48, 16, v46
	s_waitcnt lgkmcnt(0)
	v_add_f32_e32 v81, v49, v50
	ds_bpermute_b32 v92, v79, v81
	v_lshlrev_b32_e32 v50, 16, v47
	v_and_b32_e32 v49, 0xffff0000, v46
	v_lshlrev_b32_e32 v46, 16, v44
	s_waitcnt lgkmcnt(0)
	v_add_f32_e32 v47, v81, v92
	v_fmamk_f32 v47, v47, 0x3a000000, v80
	v_mul_f32_e32 v81, 0x4b800000, v47
	v_cmp_gt_f32_e32 vcc, s6, v47
	v_lshlrev_b32_e32 v92, 16, v45
	s_nop 0
	v_cndmask_b32_e32 v47, v47, v81, vcc
	v_rsq_f32_e32 v81, v47
	v_and_b32_e32 v47, 0xffff0000, v44
	v_mul_f32_e32 v44, 0x45800000, v81
	v_cndmask_b32_e32 v94, v81, v44, vcc
	v_pk_mul_f32 v[44:45], v[94:95], v[96:97] op_sel_hi:[0,1]
	v_pk_fma_f32 v[44:45], v[170:171], v[44:45], v[46:47]
	v_pk_mul_f32 v[46:47], v[94:95], v[90:91] op_sel_hi:[0,1]
	v_pk_fma_f32 v[48:49], v[174:175], v[46:47], v[48:49]
	v_pk_mul_f32 v[46:47], v[94:95], v[60:61] op_sel_hi:[0,1]
	v_pk_mul_f32 v[60:61], v[94:95], v[62:63] op_sel_hi:[0,1]
	v_pk_fma_f32 v[50:51], v[176:177], v[60:61], v[50:51]
	v_add_co_u32_e32 v60, vcc, s7, v70
	v_pk_fma_f32 v[46:47], v[172:173], v[46:47], v[92:93]
	s_nop 0
	v_addc_co_u32_e32 v61, vcc, -1, v71, vcc
	s_waitcnt vmcnt(0)
	global_store_dwordx4 v[60:61], v[44:47], off offset:-2064 nt
	global_store_dwordx4 v[60:61], v[48:51], off offset:-2048 nt
	v_lshlrev_b32_e32 v62, 16, v42
	v_and_b32_e32 v63, 0xffff0000, v42
	v_lshlrev_b32_e32 v82, 16, v43
	v_and_b32_e32 v83, 0xffff0000, v43
	v_lshlrev_b32_e32 v42, 16, v40
	v_and_b32_e32 v43, 0xffff0000, v40
	v_lshlrev_b32_e32 v84, 16, v41
	v_and_b32_e32 v85, 0xffff0000, v41
	v_pk_mul_f32 v[40:41], v[94:95], v[108:109] op_sel_hi:[0,1]
	v_pk_mul_f32 v[56:57], v[94:95], v[56:57] op_sel_hi:[0,1]
	v_pk_mul_f32 v[86:87], v[94:95], v[102:103] op_sel_hi:[0,1]
	v_pk_mul_f32 v[58:59], v[94:95], v[58:59] op_sel_hi:[0,1]
	v_pk_mul_f32 v[52:53], v[94:95], v[52:53] op_sel_hi:[0,1]
	v_pk_mul_f32 v[54:55], v[94:95], v[54:55] op_sel_hi:[0,1]
	v_lshlrev_b32_e32 v90, 16, v0
	v_and_b32_e32 v91, 0xffff0000, v0
	v_lshlrev_b32_e32 v92, 16, v1
	v_and_b32_e32 v93, 0xffff0000, v1
	v_pk_mul_f32 v[96:97], v[94:95], v[132:133] op_sel_hi:[0,1]
	v_pk_mul_f32 v[100:101], v[94:95], v[136:137] op_sel_hi:[0,1]
	v_lshlrev_b32_e32 v88, 16, v3
	v_and_b32_e32 v89, 0xffff0000, v3
	v_pk_mul_f32 v[98:99], v[94:95], v[126:127] op_sel_hi:[0,1]
	s_andn2_b64 vcc, exec, s[4:5]
	v_pk_fma_f32 v[40:41], v[178:179], v[40:41], v[42:43]
	v_pk_fma_f32 v[42:43], v[180:181], v[56:57], v[84:85]
	v_pk_fma_f32 v[44:45], v[182:183], v[86:87], v[62:63]
	v_pk_fma_f32 v[46:47], v[184:185], v[58:59], v[82:83]
	global_store_dwordx4 v[60:61], v[40:43], off offset:-16 nt
	global_store_dwordx4 v[70:71], v[44:47], off offset:-4096 nt
	v_lshlrev_b32_e32 v48, 16, v6
	v_and_b32_e32 v49, 0xffff0000, v6
	v_lshlrev_b32_e32 v50, 16, v7
	v_and_b32_e32 v51, 0xffff0000, v7
	v_lshlrev_b32_e32 v6, 16, v4
	v_and_b32_e32 v7, 0xffff0000, v4
	v_lshlrev_b32_e32 v56, 16, v5
	v_and_b32_e32 v57, 0xffff0000, v5
	v_pk_mul_f32 v[4:5], v[94:95], v[120:121] op_sel_hi:[0,1]
	v_pk_mul_f32 v[58:59], v[94:95], v[114:115] op_sel_hi:[0,1]
	v_lshlrev_b32_e32 v86, 16, v2
	v_and_b32_e32 v87, 0xffff0000, v2
	v_pk_mul_f32 v[94:95], v[94:95], v[130:131] op_sel_hi:[0,1]
	v_mov_b64_e32 v[62:63], v[22:23]
	v_mov_b64_e32 v[0:1], v[24:25]
	v_mov_b64_e32 v[60:61], v[20:21]
	v_mov_b64_e32 v[2:3], v[26:27]
	v_pk_fma_f32 v[4:5], v[186:187], v[4:5], v[6:7]
	v_pk_fma_f32 v[6:7], v[188:189], v[52:53], v[56:57]
	v_pk_fma_f32 v[40:41], v[190:191], v[58:59], v[48:49]
	v_pk_fma_f32 v[42:43], v[192:193], v[54:55], v[50:51]
	global_store_dwordx4 v[70:71], v[4:7], off offset:-2064 nt
	global_store_dwordx4 v[70:71], v[40:43], off offset:-2048 nt
	v_mov_b64_e32 v[50:51], v[10:11]
	v_mov_b64_e32 v[54:55], v[14:15]
	v_mov_b64_e32 v[58:59], v[18:19]
	v_mov_b64_e32 v[4:5], v[28:29]
	v_mov_b64_e32 v[42:43], v[34:35]
	v_mov_b64_e32 v[48:49], v[8:9]
	v_mov_b64_e32 v[52:53], v[12:13]
	v_mov_b64_e32 v[56:57], v[16:17]
	v_mov_b64_e32 v[6:7], v[30:31]
	v_mov_b64_e32 v[40:41], v[32:33]
	v_pk_fma_f32 v[44:45], v[194:195], v[96:97], v[90:91]
	v_pk_fma_f32 v[46:47], v[196:197], v[100:101], v[92:93]
	v_pk_fma_f32 v[82:83], v[198:199], v[98:99], v[86:87]
	v_pk_fma_f32 v[84:85], v[200:201], v[94:95], v[88:89]
	global_store_dwordx4 v[70:71], v[44:47], off offset:-16 nt
	global_store_dwordx4 v[70:71], v[82:85], off nt
	v_lshl_add_u64 v[70:71], v[70:71], 0, s[0:1]
	v_mov_b64_e32 v[46:47], v[38:39]
	v_mov_b64_e32 v[44:45], v[36:37]
	s_cbranch_vccz .LBB0_1399
.LBB0_1397:
	s_add_i32 s86, s86, s34
	s_cmp_gt_i32 s86, 0x83ff
	s_cselect_b64 s[4:5], -1, 0
	s_and_b64 vcc, exec, s[4:5]
	s_cbranch_vccnz .LBB0_1396
	v_add_co_u32_e32 v82, vcc, 0xf2900000, v72
	global_load_dwordx4 v[20:23], v[72:73], off offset:-3072 nt
	global_load_dwordx4 v[16:19], v[72:73], off offset:-2048 nt
	global_load_dwordx4 v[12:15], v[72:73], off offset:-1024 nt
	global_load_dwordx4 v[8:11], v[72:73], off nt
	v_addc_co_u32_e32 v83, vcc, -1, v73, vcc
	global_load_dwordx4 v[36:39], v[82:83], off offset:-3072 nt
	global_load_dwordx4 v[32:35], v[82:83], off offset:-2048 nt
	global_load_dwordx4 v[28:31], v[82:83], off offset:-1024 nt
	global_load_dwordx4 v[24:27], v[82:83], off nt
	s_branch .LBB0_1396
